# in-proj silu gate-tile epilogue rewritten with packed f32 (v_pk_mul/add) for the non-transcendental half; these tiles sit on the 9-tile workgroups' critical path
# baseline (speedup 1.0000x reference)
; __device__ __forceinline__ unsigned cvt_pk_bf16(float lo, float hi) { unsigned r; asm volatile("v_cvt_pk_bf16_f32 %0, %1, %2" : "=v"(r) : "v"(lo), "v"(hi)); return r; }
; __device__ __forceinline__ float siluf_(float v) { return v * __builtin_amdgcn_rcpf(1.f + __expf(-v)); }
;     __device__ __forceinline__ void operator()(const f32x4 (&acc)[2][2][4][2], const pg8::Unit& u, int wr, int wc, int fr, int fq) const {
;     ...
;             bf16_t* D = (bf16_t*)(ws + (pn < 10 ? WS_GA : WS_GB));
;             const int colb = 256 * (pn < 10 ? pn - 8 : pn - 14) + 32 * wc + 8 * fq;
; #pragma unroll
;             for (int ai = 0; ai < 2; ++ai)
; #pragma unroll
;                 for (int m = 0; m < 4; ++m) {
;                     const size_t row = (size_t)(row0 + ai * 128 + m * 16);
; #pragma unroll
;                     for (int bj = 0; bj < 2; ++bj) {
;                         f32x4 v0 = acc[ai][bj][m][0], v1 = acc[ai][bj][m][1];
; #pragma unroll
;                         for (int j = 0; j < 4; ++j) { v0[j] = siluf_(v0[j]); v1[j] = siluf_(v1[j]); }
;                         u32x4 o = {cvt_pk_bf16(v0[0], v0[1]), cvt_pk_bf16(v0[2], v0[3]), cvt_pk_bf16(v1[0], v1[1]), cvt_pk_bf16(v1[2], v1[3])};
;                         *(u32x4*)(D + row * 512 + colb + 128 * bj) = o;
;                     }
.Lgate_new:
	s_mov_b32 s4, 0xfb00000
	s_cmp_lt_u32 s10, 10
	s_cselect_b32 s4, s4, 0x13b00000
	s_cselect_b32 s5, -8, -14
	s_add_u32 s14, s70, s4
	s_addc_u32 s15, s71, 0
	s_add_i32 s4, s5, s10
	v_lshl_or_b32 v173, s4, 8, v183
	v_lshlrev_b32_e32 v173, 1, v173
	v_lshl_add_u32 v173, v172, 10, v173
	v_mov_b32_e32 v130, 0xbfb8aa3b
	v_mov_b32_e32 v131, 0xbfb8aa3b
	s_add_u32 s4, s14, 0
	s_addc_u32 s5, s15, 0
	v_pk_mul_f32 v[132:133], v[94:95], v[130:131]
	v_pk_mul_f32 v[134:135], v[96:97], v[130:131]
	v_pk_mul_f32 v[136:137], v[126:127], v[130:131]
	v_pk_mul_f32 v[138:139], v[128:129], v[130:131]
	v_exp_f32_e32 v132, v132
	v_exp_f32_e32 v133, v133
	v_exp_f32_e32 v134, v134
	v_exp_f32_e32 v135, v135
	v_exp_f32_e32 v136, v136
	v_exp_f32_e32 v137, v137
	v_exp_f32_e32 v138, v138
	v_exp_f32_e32 v139, v139
	v_pk_add_f32 v[132:133], v[132:133], 1.0 op_sel_hi:[1,0]
	v_pk_add_f32 v[134:135], v[134:135], 1.0 op_sel_hi:[1,0]
	v_pk_add_f32 v[136:137], v[136:137], 1.0 op_sel_hi:[1,0]
	v_pk_add_f32 v[138:139], v[138:139], 1.0 op_sel_hi:[1,0]
	v_rcp_f32_e32 v132, v132
	v_rcp_f32_e32 v133, v133
	v_rcp_f32_e32 v134, v134
	v_rcp_f32_e32 v135, v135
	v_rcp_f32_e32 v136, v136
	v_rcp_f32_e32 v137, v137
	v_rcp_f32_e32 v138, v138
	v_rcp_f32_e32 v139, v139
	v_pk_mul_f32 v[132:133], v[94:95], v[132:133]
	v_pk_mul_f32 v[134:135], v[96:97], v[134:135]
	v_pk_mul_f32 v[136:137], v[126:127], v[136:137]
	v_pk_mul_f32 v[138:139], v[128:129], v[138:139]
	v_cvt_pk_bf16_f32 v140, v132, v133
	v_cvt_pk_bf16_f32 v141, v134, v135
	v_cvt_pk_bf16_f32 v142, v136, v137
	v_cvt_pk_bf16_f32 v143, v138, v139
	global_store_dwordx4 v173, v[140:143], s[4:5] offset:0
	v_pk_mul_f32 v[132:133], v[122:123], v[130:131]
	v_pk_mul_f32 v[134:135], v[124:125], v[130:131]
	v_pk_mul_f32 v[136:137], v[78:79], v[130:131]
	v_pk_mul_f32 v[138:139], v[80:81], v[130:131]
	v_exp_f32_e32 v132, v132
	v_exp_f32_e32 v133, v133
	v_exp_f32_e32 v134, v134
	v_exp_f32_e32 v135, v135
	v_exp_f32_e32 v136, v136
	v_exp_f32_e32 v137, v137
	v_exp_f32_e32 v138, v138
	v_exp_f32_e32 v139, v139
	v_pk_add_f32 v[132:133], v[132:133], 1.0 op_sel_hi:[1,0]
	v_pk_add_f32 v[134:135], v[134:135], 1.0 op_sel_hi:[1,0]
	v_pk_add_f32 v[136:137], v[136:137], 1.0 op_sel_hi:[1,0]
	v_pk_add_f32 v[138:139], v[138:139], 1.0 op_sel_hi:[1,0]
	v_rcp_f32_e32 v132, v132
	v_rcp_f32_e32 v133, v133
	v_rcp_f32_e32 v134, v134
	v_rcp_f32_e32 v135, v135
	v_rcp_f32_e32 v136, v136
	v_rcp_f32_e32 v137, v137
	v_rcp_f32_e32 v138, v138
	v_rcp_f32_e32 v139, v139
	v_pk_mul_f32 v[132:133], v[122:123], v[132:133]
	v_pk_mul_f32 v[134:135], v[124:125], v[134:135]
	v_pk_mul_f32 v[136:137], v[78:79], v[136:137]
	v_pk_mul_f32 v[138:139], v[80:81], v[138:139]
	v_cvt_pk_bf16_f32 v144, v132, v133
	v_cvt_pk_bf16_f32 v145, v134, v135
	v_cvt_pk_bf16_f32 v146, v136, v137
	v_cvt_pk_bf16_f32 v147, v138, v139
	global_store_dwordx4 v173, v[144:147], s[4:5] offset:256
	s_add_u32 s4, s14, 16384
	s_addc_u32 s5, s15, 0
	v_pk_mul_f32 v[132:133], v[90:91], v[130:131]
	v_pk_mul_f32 v[134:135], v[92:93], v[130:131]
	v_pk_mul_f32 v[136:137], v[118:119], v[130:131]
	v_pk_mul_f32 v[138:139], v[120:121], v[130:131]
	v_exp_f32_e32 v132, v132
	v_exp_f32_e32 v133, v133
	v_exp_f32_e32 v134, v134
	v_exp_f32_e32 v135, v135
	v_exp_f32_e32 v136, v136
	v_exp_f32_e32 v137, v137
	v_exp_f32_e32 v138, v138
	v_exp_f32_e32 v139, v139
	v_pk_add_f32 v[132:133], v[132:133], 1.0 op_sel_hi:[1,0]
	v_pk_add_f32 v[134:135], v[134:135], 1.0 op_sel_hi:[1,0]
	v_pk_add_f32 v[136:137], v[136:137], 1.0 op_sel_hi:[1,0]
	v_pk_add_f32 v[138:139], v[138:139], 1.0 op_sel_hi:[1,0]
	v_rcp_f32_e32 v132, v132
	v_rcp_f32_e32 v133, v133
	v_rcp_f32_e32 v134, v134
	v_rcp_f32_e32 v135, v135
	v_rcp_f32_e32 v136, v136
	v_rcp_f32_e32 v137, v137
	v_rcp_f32_e32 v138, v138
	v_rcp_f32_e32 v139, v139
	v_pk_mul_f32 v[132:133], v[90:91], v[132:133]
	v_pk_mul_f32 v[134:135], v[92:93], v[134:135]
	v_pk_mul_f32 v[136:137], v[118:119], v[136:137]
	v_pk_mul_f32 v[138:139], v[120:121], v[138:139]
	v_cvt_pk_bf16_f32 v140, v132, v133
	v_cvt_pk_bf16_f32 v141, v134, v135
	v_cvt_pk_bf16_f32 v142, v136, v137
	v_cvt_pk_bf16_f32 v143, v138, v139
	global_store_dwordx4 v173, v[140:143], s[4:5] offset:0
	v_pk_mul_f32 v[132:133], v[114:115], v[130:131]
	v_pk_mul_f32 v[134:135], v[116:117], v[130:131]
	v_pk_mul_f32 v[136:137], v[74:75], v[130:131]
	v_pk_mul_f32 v[138:139], v[76:77], v[130:131]
	v_exp_f32_e32 v132, v132
	v_exp_f32_e32 v133, v133
	v_exp_f32_e32 v134, v134
	v_exp_f32_e32 v135, v135
	v_exp_f32_e32 v136, v136
	v_exp_f32_e32 v137, v137
	v_exp_f32_e32 v138, v138
	v_exp_f32_e32 v139, v139
	v_pk_add_f32 v[132:133], v[132:133], 1.0 op_sel_hi:[1,0]
	v_pk_add_f32 v[134:135], v[134:135], 1.0 op_sel_hi:[1,0]
	v_pk_add_f32 v[136:137], v[136:137], 1.0 op_sel_hi:[1,0]
	v_pk_add_f32 v[138:139], v[138:139], 1.0 op_sel_hi:[1,0]
	v_rcp_f32_e32 v132, v132
	v_rcp_f32_e32 v133, v133
	v_rcp_f32_e32 v134, v134
	v_rcp_f32_e32 v135, v135
	v_rcp_f32_e32 v136, v136
	v_rcp_f32_e32 v137, v137
	v_rcp_f32_e32 v138, v138
	v_rcp_f32_e32 v139, v139
	v_pk_mul_f32 v[132:133], v[114:115], v[132:133]
	v_pk_mul_f32 v[134:135], v[116:117], v[134:135]
	v_pk_mul_f32 v[136:137], v[74:75], v[136:137]
	v_pk_mul_f32 v[138:139], v[76:77], v[138:139]
	v_cvt_pk_bf16_f32 v144, v132, v133
	v_cvt_pk_bf16_f32 v145, v134, v135
	v_cvt_pk_bf16_f32 v146, v136, v137
	v_cvt_pk_bf16_f32 v147, v138, v139
	global_store_dwordx4 v173, v[144:147], s[4:5] offset:256
	s_add_u32 s4, s14, 32768
	s_addc_u32 s5, s15, 0
	v_pk_mul_f32 v[132:133], v[86:87], v[130:131]
	v_pk_mul_f32 v[134:135], v[88:89], v[130:131]
	v_pk_mul_f32 v[136:137], v[110:111], v[130:131]
	v_pk_mul_f32 v[138:139], v[112:113], v[130:131]
	v_exp_f32_e32 v132, v132
; __device__ __forceinline__ unsigned cvt_pk_bf16(float lo, float hi) { unsigned r; asm volatile("v_cvt_pk_bf16_f32 %0, %1, %2" : "=v"(r) : "v"(lo), "v"(hi)); return r; }
; __device__ __forceinline__ float siluf_(float v) { return v * __builtin_amdgcn_rcpf(1.f + __expf(-v)); }
;     __device__ __forceinline__ void operator()(const f32x4 (&acc)[2][2][4][2], const pg8::Unit& u, int wr, int wc, int fr, int fq) const {
;     ...
;             bf16_t* D = (bf16_t*)(ws + (pn < 10 ? WS_GA : WS_GB));
;             const int colb = 256 * (pn < 10 ? pn - 8 : pn - 14) + 32 * wc + 8 * fq;
; #pragma unroll
;             for (int ai = 0; ai < 2; ++ai)
; #pragma unroll
;                 for (int m = 0; m < 4; ++m) {
;                     const size_t row = (size_t)(row0 + ai * 128 + m * 16);
; #pragma unroll
;                     for (int bj = 0; bj < 2; ++bj) {
;                         f32x4 v0 = acc[ai][bj][m][0], v1 = acc[ai][bj][m][1];
; #pragma unroll
;                         for (int j = 0; j < 4; ++j) { v0[j] = siluf_(v0[j]); v1[j] = siluf_(v1[j]); }
;                         u32x4 o = {cvt_pk_bf16(v0[0], v0[1]), cvt_pk_bf16(v0[2], v0[3]), cvt_pk_bf16(v1[0], v1[1]), cvt_pk_bf16(v1[2], v1[3])};
;                         *(u32x4*)(D + row * 512 + colb + 128 * bj) = o;
;                     }
	v_exp_f32_e32 v133, v133
	v_exp_f32_e32 v134, v134
	v_exp_f32_e32 v135, v135
	v_exp_f32_e32 v136, v136
	v_exp_f32_e32 v137, v137
	v_exp_f32_e32 v138, v138
	v_exp_f32_e32 v139, v139
	v_pk_add_f32 v[132:133], v[132:133], 1.0 op_sel_hi:[1,0]
	v_pk_add_f32 v[134:135], v[134:135], 1.0 op_sel_hi:[1,0]
	v_pk_add_f32 v[136:137], v[136:137], 1.0 op_sel_hi:[1,0]
	v_pk_add_f32 v[138:139], v[138:139], 1.0 op_sel_hi:[1,0]
	v_rcp_f32_e32 v132, v132
	v_rcp_f32_e32 v133, v133
	v_rcp_f32_e32 v134, v134
	v_rcp_f32_e32 v135, v135
	v_rcp_f32_e32 v136, v136
	v_rcp_f32_e32 v137, v137
	v_rcp_f32_e32 v138, v138
	v_rcp_f32_e32 v139, v139
	v_pk_mul_f32 v[132:133], v[86:87], v[132:133]
	v_pk_mul_f32 v[134:135], v[88:89], v[134:135]
	v_pk_mul_f32 v[136:137], v[110:111], v[136:137]
	v_pk_mul_f32 v[138:139], v[112:113], v[138:139]
	v_cvt_pk_bf16_f32 v140, v132, v133
	v_cvt_pk_bf16_f32 v141, v134, v135
	v_cvt_pk_bf16_f32 v142, v136, v137
	v_cvt_pk_bf16_f32 v143, v138, v139
	global_store_dwordx4 v173, v[140:143], s[4:5] offset:0
	v_pk_mul_f32 v[132:133], v[106:107], v[130:131]
	v_pk_mul_f32 v[134:135], v[108:109], v[130:131]
	v_pk_mul_f32 v[136:137], v[70:71], v[130:131]
	v_pk_mul_f32 v[138:139], v[72:73], v[130:131]
	v_exp_f32_e32 v132, v132
	v_exp_f32_e32 v133, v133
	v_exp_f32_e32 v134, v134
	v_exp_f32_e32 v135, v135
	v_exp_f32_e32 v136, v136
	v_exp_f32_e32 v137, v137
	v_exp_f32_e32 v138, v138
	v_exp_f32_e32 v139, v139
	v_pk_add_f32 v[132:133], v[132:133], 1.0 op_sel_hi:[1,0]
	v_pk_add_f32 v[134:135], v[134:135], 1.0 op_sel_hi:[1,0]
	v_pk_add_f32 v[136:137], v[136:137], 1.0 op_sel_hi:[1,0]
	v_pk_add_f32 v[138:139], v[138:139], 1.0 op_sel_hi:[1,0]
	v_rcp_f32_e32 v132, v132
	v_rcp_f32_e32 v133, v133
	v_rcp_f32_e32 v134, v134
	v_rcp_f32_e32 v135, v135
	v_rcp_f32_e32 v136, v136
	v_rcp_f32_e32 v137, v137
	v_rcp_f32_e32 v138, v138
	v_rcp_f32_e32 v139, v139
	v_pk_mul_f32 v[132:133], v[106:107], v[132:133]
	v_pk_mul_f32 v[134:135], v[108:109], v[134:135]
	v_pk_mul_f32 v[136:137], v[70:71], v[136:137]
	v_pk_mul_f32 v[138:139], v[72:73], v[138:139]
	v_cvt_pk_bf16_f32 v144, v132, v133
	v_cvt_pk_bf16_f32 v145, v134, v135
	v_cvt_pk_bf16_f32 v146, v136, v137
	v_cvt_pk_bf16_f32 v147, v138, v139
	global_store_dwordx4 v173, v[144:147], s[4:5] offset:256
	s_add_u32 s4, s14, 49152
	s_addc_u32 s5, s15, 0
	v_pk_mul_f32 v[132:133], v[82:83], v[130:131]
	v_pk_mul_f32 v[134:135], v[84:85], v[130:131]
	v_pk_mul_f32 v[136:137], v[102:103], v[130:131]
	v_pk_mul_f32 v[138:139], v[104:105], v[130:131]
	v_exp_f32_e32 v132, v132
	v_exp_f32_e32 v133, v133
	v_exp_f32_e32 v134, v134
	v_exp_f32_e32 v135, v135
	v_exp_f32_e32 v136, v136
	v_exp_f32_e32 v137, v137
	v_exp_f32_e32 v138, v138
	v_exp_f32_e32 v139, v139
	v_pk_add_f32 v[132:133], v[132:133], 1.0 op_sel_hi:[1,0]
	v_pk_add_f32 v[134:135], v[134:135], 1.0 op_sel_hi:[1,0]
	v_pk_add_f32 v[136:137], v[136:137], 1.0 op_sel_hi:[1,0]
	v_pk_add_f32 v[138:139], v[138:139], 1.0 op_sel_hi:[1,0]
	v_rcp_f32_e32 v132, v132
	v_rcp_f32_e32 v133, v133
	v_rcp_f32_e32 v134, v134
	v_rcp_f32_e32 v135, v135
	v_rcp_f32_e32 v136, v136
	v_rcp_f32_e32 v137, v137
	v_rcp_f32_e32 v138, v138
	v_rcp_f32_e32 v139, v139
	v_pk_mul_f32 v[132:133], v[82:83], v[132:133]
	v_pk_mul_f32 v[134:135], v[84:85], v[134:135]
	v_pk_mul_f32 v[136:137], v[102:103], v[136:137]
	v_pk_mul_f32 v[138:139], v[104:105], v[138:139]
	v_cvt_pk_bf16_f32 v140, v132, v133
	v_cvt_pk_bf16_f32 v141, v134, v135
	v_cvt_pk_bf16_f32 v142, v136, v137
	v_cvt_pk_bf16_f32 v143, v138, v139
	global_store_dwordx4 v173, v[140:143], s[4:5] offset:0
	v_pk_mul_f32 v[132:133], v[98:99], v[130:131]
	v_pk_mul_f32 v[134:135], v[100:101], v[130:131]
	v_pk_mul_f32 v[136:137], v[66:67], v[130:131]
	v_pk_mul_f32 v[138:139], v[68:69], v[130:131]
	v_exp_f32_e32 v132, v132
	v_exp_f32_e32 v133, v133
	v_exp_f32_e32 v134, v134
	v_exp_f32_e32 v135, v135
	v_exp_f32_e32 v136, v136
	v_exp_f32_e32 v137, v137
	v_exp_f32_e32 v138, v138
	v_exp_f32_e32 v139, v139
	v_pk_add_f32 v[132:133], v[132:133], 1.0 op_sel_hi:[1,0]
	v_pk_add_f32 v[134:135], v[134:135], 1.0 op_sel_hi:[1,0]
	v_pk_add_f32 v[136:137], v[136:137], 1.0 op_sel_hi:[1,0]
	v_pk_add_f32 v[138:139], v[138:139], 1.0 op_sel_hi:[1,0]
	v_rcp_f32_e32 v132, v132
	v_rcp_f32_e32 v133, v133
	v_rcp_f32_e32 v134, v134
	v_rcp_f32_e32 v135, v135
	v_rcp_f32_e32 v136, v136
	v_rcp_f32_e32 v137, v137
	v_rcp_f32_e32 v138, v138
	v_rcp_f32_e32 v139, v139
	v_pk_mul_f32 v[132:133], v[98:99], v[132:133]
	v_pk_mul_f32 v[134:135], v[100:101], v[134:135]
	v_pk_mul_f32 v[136:137], v[66:67], v[136:137]
	v_pk_mul_f32 v[138:139], v[68:69], v[138:139]
	v_cvt_pk_bf16_f32 v144, v132, v133
	v_cvt_pk_bf16_f32 v145, v134, v135
	v_cvt_pk_bf16_f32 v146, v136, v137
	v_cvt_pk_bf16_f32 v147, v138, v139
	global_store_dwordx4 v173, v[144:147], s[4:5] offset:256
	s_add_u32 s4, s14, 131072
	s_addc_u32 s5, s15, 0
	v_pk_mul_f32 v[132:133], v[30:31], v[130:131]
	v_pk_mul_f32 v[134:135], v[32:33], v[130:131]
	v_pk_mul_f32 v[136:137], v[62:63], v[130:131]
	v_pk_mul_f32 v[138:139], v[64:65], v[130:131]
	v_exp_f32_e32 v132, v132
	v_exp_f32_e32 v133, v133
	v_exp_f32_e32 v134, v134
	v_exp_f32_e32 v135, v135
	v_exp_f32_e32 v136, v136
	v_exp_f32_e32 v137, v137
	v_exp_f32_e32 v138, v138
	v_exp_f32_e32 v139, v139
	v_pk_add_f32 v[132:133], v[132:133], 1.0 op_sel_hi:[1,0]
	v_pk_add_f32 v[134:135], v[134:135], 1.0 op_sel_hi:[1,0]
	v_pk_add_f32 v[136:137], v[136:137], 1.0 op_sel_hi:[1,0]
	v_pk_add_f32 v[138:139], v[138:139], 1.0 op_sel_hi:[1,0]
	v_rcp_f32_e32 v132, v132
	v_rcp_f32_e32 v133, v133
	v_rcp_f32_e32 v134, v134
	v_rcp_f32_e32 v135, v135
	v_rcp_f32_e32 v136, v136
	v_rcp_f32_e32 v137, v137
	v_rcp_f32_e32 v138, v138
	v_rcp_f32_e32 v139, v139
; __device__ __forceinline__ unsigned cvt_pk_bf16(float lo, float hi) { unsigned r; asm volatile("v_cvt_pk_bf16_f32 %0, %1, %2" : "=v"(r) : "v"(lo), "v"(hi)); return r; }
; __device__ __forceinline__ float siluf_(float v) { return v * __builtin_amdgcn_rcpf(1.f + __expf(-v)); }
;     __device__ __forceinline__ void operator()(const f32x4 (&acc)[2][2][4][2], const pg8::Unit& u, int wr, int wc, int fr, int fq) const {
;     ...
;             bf16_t* D = (bf16_t*)(ws + (pn < 10 ? WS_GA : WS_GB));
;             const int colb = 256 * (pn < 10 ? pn - 8 : pn - 14) + 32 * wc + 8 * fq;
; #pragma unroll
;             for (int ai = 0; ai < 2; ++ai)
; #pragma unroll
;                 for (int m = 0; m < 4; ++m) {
;                     const size_t row = (size_t)(row0 + ai * 128 + m * 16);
; #pragma unroll
;                     for (int bj = 0; bj < 2; ++bj) {
;                         f32x4 v0 = acc[ai][bj][m][0], v1 = acc[ai][bj][m][1];
; #pragma unroll
;                         for (int j = 0; j < 4; ++j) { v0[j] = siluf_(v0[j]); v1[j] = siluf_(v1[j]); }
;                         u32x4 o = {cvt_pk_bf16(v0[0], v0[1]), cvt_pk_bf16(v0[2], v0[3]), cvt_pk_bf16(v1[0], v1[1]), cvt_pk_bf16(v1[2], v1[3])};
;                         *(u32x4*)(D + row * 512 + colb + 128 * bj) = o;
;                     }
	v_pk_mul_f32 v[132:133], v[30:31], v[132:133]
	v_pk_mul_f32 v[134:135], v[32:33], v[134:135]
	v_pk_mul_f32 v[136:137], v[62:63], v[136:137]
	v_pk_mul_f32 v[138:139], v[64:65], v[138:139]
	v_cvt_pk_bf16_f32 v140, v132, v133
	v_cvt_pk_bf16_f32 v141, v134, v135
	v_cvt_pk_bf16_f32 v142, v136, v137
	v_cvt_pk_bf16_f32 v143, v138, v139
	global_store_dwordx4 v173, v[140:143], s[4:5] offset:0
	v_pk_mul_f32 v[132:133], v[58:59], v[130:131]
	v_pk_mul_f32 v[134:135], v[60:61], v[130:131]
	v_pk_mul_f32 v[136:137], v[14:15], v[130:131]
	v_pk_mul_f32 v[138:139], v[16:17], v[130:131]
	v_exp_f32_e32 v132, v132
	v_exp_f32_e32 v133, v133
	v_exp_f32_e32 v134, v134
	v_exp_f32_e32 v135, v135
	v_exp_f32_e32 v136, v136
	v_exp_f32_e32 v137, v137
	v_exp_f32_e32 v138, v138
	v_exp_f32_e32 v139, v139
	v_pk_add_f32 v[132:133], v[132:133], 1.0 op_sel_hi:[1,0]
	v_pk_add_f32 v[134:135], v[134:135], 1.0 op_sel_hi:[1,0]
	v_pk_add_f32 v[136:137], v[136:137], 1.0 op_sel_hi:[1,0]
	v_pk_add_f32 v[138:139], v[138:139], 1.0 op_sel_hi:[1,0]
	v_rcp_f32_e32 v132, v132
	v_rcp_f32_e32 v133, v133
	v_rcp_f32_e32 v134, v134
	v_rcp_f32_e32 v135, v135
	v_rcp_f32_e32 v136, v136
	v_rcp_f32_e32 v137, v137
	v_rcp_f32_e32 v138, v138
	v_rcp_f32_e32 v139, v139
	v_pk_mul_f32 v[132:133], v[58:59], v[132:133]
	v_pk_mul_f32 v[134:135], v[60:61], v[134:135]
	v_pk_mul_f32 v[136:137], v[14:15], v[136:137]
	v_pk_mul_f32 v[138:139], v[16:17], v[138:139]
	v_cvt_pk_bf16_f32 v144, v132, v133
	v_cvt_pk_bf16_f32 v145, v134, v135
	v_cvt_pk_bf16_f32 v146, v136, v137
	v_cvt_pk_bf16_f32 v147, v138, v139
	global_store_dwordx4 v173, v[144:147], s[4:5] offset:256
	s_add_u32 s4, s14, 147456
	s_addc_u32 s5, s15, 0
	v_pk_mul_f32 v[132:133], v[26:27], v[130:131]
	v_pk_mul_f32 v[134:135], v[28:29], v[130:131]
	v_pk_mul_f32 v[136:137], v[54:55], v[130:131]
	v_pk_mul_f32 v[138:139], v[56:57], v[130:131]
	v_exp_f32_e32 v132, v132
	v_exp_f32_e32 v133, v133
	v_exp_f32_e32 v134, v134
	v_exp_f32_e32 v135, v135
	v_exp_f32_e32 v136, v136
	v_exp_f32_e32 v137, v137
	v_exp_f32_e32 v138, v138
	v_exp_f32_e32 v139, v139
	v_pk_add_f32 v[132:133], v[132:133], 1.0 op_sel_hi:[1,0]
	v_pk_add_f32 v[134:135], v[134:135], 1.0 op_sel_hi:[1,0]
	v_pk_add_f32 v[136:137], v[136:137], 1.0 op_sel_hi:[1,0]
	v_pk_add_f32 v[138:139], v[138:139], 1.0 op_sel_hi:[1,0]
	v_rcp_f32_e32 v132, v132
	v_rcp_f32_e32 v133, v133
	v_rcp_f32_e32 v134, v134
	v_rcp_f32_e32 v135, v135
	v_rcp_f32_e32 v136, v136
	v_rcp_f32_e32 v137, v137
	v_rcp_f32_e32 v138, v138
	v_rcp_f32_e32 v139, v139
	v_pk_mul_f32 v[132:133], v[26:27], v[132:133]
	v_pk_mul_f32 v[134:135], v[28:29], v[134:135]
	v_pk_mul_f32 v[136:137], v[54:55], v[136:137]
	v_pk_mul_f32 v[138:139], v[56:57], v[138:139]
	v_cvt_pk_bf16_f32 v140, v132, v133
	v_cvt_pk_bf16_f32 v141, v134, v135
	v_cvt_pk_bf16_f32 v142, v136, v137
	v_cvt_pk_bf16_f32 v143, v138, v139
	global_store_dwordx4 v173, v[140:143], s[4:5] offset:0
	v_pk_mul_f32 v[132:133], v[50:51], v[130:131]
	v_pk_mul_f32 v[134:135], v[52:53], v[130:131]
	v_pk_mul_f32 v[136:137], v[10:11], v[130:131]
	v_pk_mul_f32 v[138:139], v[12:13], v[130:131]
	v_exp_f32_e32 v132, v132
	v_exp_f32_e32 v133, v133
	v_exp_f32_e32 v134, v134
	v_exp_f32_e32 v135, v135
	v_exp_f32_e32 v136, v136
	v_exp_f32_e32 v137, v137
	v_exp_f32_e32 v138, v138
	v_exp_f32_e32 v139, v139
	v_pk_add_f32 v[132:133], v[132:133], 1.0 op_sel_hi:[1,0]
	v_pk_add_f32 v[134:135], v[134:135], 1.0 op_sel_hi:[1,0]
	v_pk_add_f32 v[136:137], v[136:137], 1.0 op_sel_hi:[1,0]
	v_pk_add_f32 v[138:139], v[138:139], 1.0 op_sel_hi:[1,0]
	v_rcp_f32_e32 v132, v132
	v_rcp_f32_e32 v133, v133
	v_rcp_f32_e32 v134, v134
	v_rcp_f32_e32 v135, v135
	v_rcp_f32_e32 v136, v136
	v_rcp_f32_e32 v137, v137
	v_rcp_f32_e32 v138, v138
	v_rcp_f32_e32 v139, v139
	v_pk_mul_f32 v[132:133], v[50:51], v[132:133]
	v_pk_mul_f32 v[134:135], v[52:53], v[134:135]
	v_pk_mul_f32 v[136:137], v[10:11], v[136:137]
	v_pk_mul_f32 v[138:139], v[12:13], v[138:139]
	v_cvt_pk_bf16_f32 v144, v132, v133
	v_cvt_pk_bf16_f32 v145, v134, v135
	v_cvt_pk_bf16_f32 v146, v136, v137
	v_cvt_pk_bf16_f32 v147, v138, v139
	global_store_dwordx4 v173, v[144:147], s[4:5] offset:256
	s_add_u32 s4, s14, 163840
	s_addc_u32 s5, s15, 0
	v_pk_mul_f32 v[132:133], v[22:23], v[130:131]
	v_pk_mul_f32 v[134:135], v[24:25], v[130:131]
	v_pk_mul_f32 v[136:137], v[46:47], v[130:131]
	v_pk_mul_f32 v[138:139], v[48:49], v[130:131]
	v_exp_f32_e32 v132, v132
	v_exp_f32_e32 v133, v133
	v_exp_f32_e32 v134, v134
	v_exp_f32_e32 v135, v135
	v_exp_f32_e32 v136, v136
	v_exp_f32_e32 v137, v137
	v_exp_f32_e32 v138, v138
	v_exp_f32_e32 v139, v139
	v_pk_add_f32 v[132:133], v[132:133], 1.0 op_sel_hi:[1,0]
	v_pk_add_f32 v[134:135], v[134:135], 1.0 op_sel_hi:[1,0]
	v_pk_add_f32 v[136:137], v[136:137], 1.0 op_sel_hi:[1,0]
	v_pk_add_f32 v[138:139], v[138:139], 1.0 op_sel_hi:[1,0]
	v_rcp_f32_e32 v132, v132
	v_rcp_f32_e32 v133, v133
	v_rcp_f32_e32 v134, v134
	v_rcp_f32_e32 v135, v135
	v_rcp_f32_e32 v136, v136
	v_rcp_f32_e32 v137, v137
	v_rcp_f32_e32 v138, v138
	v_rcp_f32_e32 v139, v139
	v_pk_mul_f32 v[132:133], v[22:23], v[132:133]
	v_pk_mul_f32 v[134:135], v[24:25], v[134:135]
	v_pk_mul_f32 v[136:137], v[46:47], v[136:137]
	v_pk_mul_f32 v[138:139], v[48:49], v[138:139]
	v_cvt_pk_bf16_f32 v140, v132, v133
	v_cvt_pk_bf16_f32 v141, v134, v135
	v_cvt_pk_bf16_f32 v142, v136, v137
	v_cvt_pk_bf16_f32 v143, v138, v139
	global_store_dwordx4 v173, v[140:143], s[4:5] offset:0
	v_pk_mul_f32 v[132:133], v[42:43], v[130:131]
	v_pk_mul_f32 v[134:135], v[44:45], v[130:131]
	v_pk_mul_f32 v[136:137], v[6:7], v[130:131]
	v_pk_mul_f32 v[138:139], v[8:9], v[130:131]
	v_exp_f32_e32 v132, v132
	v_exp_f32_e32 v133, v133
	v_exp_f32_e32 v134, v134
; __device__ __forceinline__ unsigned cvt_pk_bf16(float lo, float hi) { unsigned r; asm volatile("v_cvt_pk_bf16_f32 %0, %1, %2" : "=v"(r) : "v"(lo), "v"(hi)); return r; }
; __device__ __forceinline__ float sigmoidf_(float v) { return __builtin_amdgcn_rcpf(1.f + __expf(-v)); }
; __device__ __forceinline__ float siluf_(float v) { return v * __builtin_amdgcn_rcpf(1.f + __expf(-v)); }
;     __device__ __forceinline__ void operator()(const f32x4 (&acc)[2][2][4][2], const pg8::Unit& u, int wr, int wc, int fr, int fq) const {
;     ...
;                         const f32x4 ua = acc[ai][bj][2 * mp][0], ga = acc[ai][bj][2 * mp][1], ub = acc[ai][bj][2 * mp + 1][0], gb = acc[ai][bj][2 * mp + 1][1];
;                         const unsigned a0 = cvt_pk_bf16(ua[0] * sigmoidf_(ga[0]), ua[1] * sigmoidf_(ga[1])), a1 = cvt_pk_bf16(ua[2] * sigmoidf_(ga[2]), ua[3] * sigmoidf_(ga[3]));
;                         const unsigned b0 = cvt_pk_bf16(ub[0] * sigmoidf_(gb[0]), ub[1] * sigmoidf_(gb[1])), b1 = cvt_pk_bf16(ub[2] * sigmoidf_(gb[2]), ub[3] * sigmoidf_(gb[3]));
;     ...
;             bf16_t* D = (bf16_t*)(ws + (pn < 10 ? WS_GA : WS_GB));
;             const int colb = 256 * (pn < 10 ? pn - 8 : pn - 14) + 32 * wc + 8 * fq;
; #pragma unroll
;             for (int ai = 0; ai < 2; ++ai)
; #pragma unroll
;                 for (int m = 0; m < 4; ++m) {
;                     const size_t row = (size_t)(row0 + ai * 128 + m * 16);
; #pragma unroll
;                     for (int bj = 0; bj < 2; ++bj) {
;                         f32x4 v0 = acc[ai][bj][m][0], v1 = acc[ai][bj][m][1];
; #pragma unroll
;                         for (int j = 0; j < 4; ++j) { v0[j] = siluf_(v0[j]); v1[j] = siluf_(v1[j]); }
;                         u32x4 o = {cvt_pk_bf16(v0[0], v0[1]), cvt_pk_bf16(v0[2], v0[3]), cvt_pk_bf16(v1[0], v1[1]), cvt_pk_bf16(v1[2], v1[3])};
;                         *(u32x4*)(D + row * 512 + colb + 128 * bj) = o;
;                     }
	v_exp_f32_e32 v135, v135
	v_exp_f32_e32 v136, v136
	v_exp_f32_e32 v137, v137
	v_exp_f32_e32 v138, v138
	v_exp_f32_e32 v139, v139
	v_pk_add_f32 v[132:133], v[132:133], 1.0 op_sel_hi:[1,0]
	v_pk_add_f32 v[134:135], v[134:135], 1.0 op_sel_hi:[1,0]
	v_pk_add_f32 v[136:137], v[136:137], 1.0 op_sel_hi:[1,0]
	v_pk_add_f32 v[138:139], v[138:139], 1.0 op_sel_hi:[1,0]
	v_rcp_f32_e32 v132, v132
	v_rcp_f32_e32 v133, v133
	v_rcp_f32_e32 v134, v134
	v_rcp_f32_e32 v135, v135
	v_rcp_f32_e32 v136, v136
	v_rcp_f32_e32 v137, v137
	v_rcp_f32_e32 v138, v138
	v_rcp_f32_e32 v139, v139
	v_pk_mul_f32 v[132:133], v[42:43], v[132:133]
	v_pk_mul_f32 v[134:135], v[44:45], v[134:135]
	v_pk_mul_f32 v[136:137], v[6:7], v[136:137]
	v_pk_mul_f32 v[138:139], v[8:9], v[138:139]
	v_cvt_pk_bf16_f32 v144, v132, v133
	v_cvt_pk_bf16_f32 v145, v134, v135
	v_cvt_pk_bf16_f32 v146, v136, v137
	v_cvt_pk_bf16_f32 v147, v138, v139
	global_store_dwordx4 v173, v[144:147], s[4:5] offset:256
	s_add_u32 s4, s14, 180224
	s_addc_u32 s5, s15, 0
	v_pk_mul_f32 v[132:133], v[18:19], v[130:131]
	v_pk_mul_f32 v[134:135], v[20:21], v[130:131]
	v_pk_mul_f32 v[136:137], v[38:39], v[130:131]
	v_pk_mul_f32 v[138:139], v[40:41], v[130:131]
	v_exp_f32_e32 v132, v132
	v_exp_f32_e32 v133, v133
	v_exp_f32_e32 v134, v134
	v_exp_f32_e32 v135, v135
	v_exp_f32_e32 v136, v136
	v_exp_f32_e32 v137, v137
	v_exp_f32_e32 v138, v138
	v_exp_f32_e32 v139, v139
	v_pk_add_f32 v[132:133], v[132:133], 1.0 op_sel_hi:[1,0]
	v_pk_add_f32 v[134:135], v[134:135], 1.0 op_sel_hi:[1,0]
	v_pk_add_f32 v[136:137], v[136:137], 1.0 op_sel_hi:[1,0]
	v_pk_add_f32 v[138:139], v[138:139], 1.0 op_sel_hi:[1,0]
	v_rcp_f32_e32 v132, v132
	v_rcp_f32_e32 v133, v133
	v_rcp_f32_e32 v134, v134
	v_rcp_f32_e32 v135, v135
	v_rcp_f32_e32 v136, v136
	v_rcp_f32_e32 v137, v137
	v_rcp_f32_e32 v138, v138
	v_rcp_f32_e32 v139, v139
	v_pk_mul_f32 v[132:133], v[18:19], v[132:133]
	v_pk_mul_f32 v[134:135], v[20:21], v[134:135]
	v_pk_mul_f32 v[136:137], v[38:39], v[136:137]
	v_pk_mul_f32 v[138:139], v[40:41], v[138:139]
	v_cvt_pk_bf16_f32 v140, v132, v133
	v_cvt_pk_bf16_f32 v141, v134, v135
	v_cvt_pk_bf16_f32 v142, v136, v137
	v_cvt_pk_bf16_f32 v143, v138, v139
	global_store_dwordx4 v173, v[140:143], s[4:5] offset:0
	v_pk_mul_f32 v[132:133], v[34:35], v[130:131]
	v_pk_mul_f32 v[134:135], v[36:37], v[130:131]
	v_pk_mul_f32 v[136:137], v[2:3], v[130:131]
	v_pk_mul_f32 v[138:139], v[4:5], v[130:131]
	v_exp_f32_e32 v132, v132
	v_exp_f32_e32 v133, v133
	v_exp_f32_e32 v134, v134
	v_exp_f32_e32 v135, v135
	v_exp_f32_e32 v136, v136
	v_exp_f32_e32 v137, v137
	v_exp_f32_e32 v138, v138
	v_exp_f32_e32 v139, v139
	v_pk_add_f32 v[132:133], v[132:133], 1.0 op_sel_hi:[1,0]
	v_pk_add_f32 v[134:135], v[134:135], 1.0 op_sel_hi:[1,0]
	v_pk_add_f32 v[136:137], v[136:137], 1.0 op_sel_hi:[1,0]
	v_pk_add_f32 v[138:139], v[138:139], 1.0 op_sel_hi:[1,0]
	v_rcp_f32_e32 v132, v132
	v_rcp_f32_e32 v133, v133
	v_rcp_f32_e32 v134, v134
	v_rcp_f32_e32 v135, v135
	v_rcp_f32_e32 v136, v136
	v_rcp_f32_e32 v137, v137
	v_rcp_f32_e32 v138, v138
	v_rcp_f32_e32 v139, v139
	v_pk_mul_f32 v[132:133], v[34:35], v[132:133]
	v_pk_mul_f32 v[134:135], v[36:37], v[134:135]
	v_pk_mul_f32 v[136:137], v[2:3], v[136:137]
	v_pk_mul_f32 v[138:139], v[4:5], v[138:139]
	v_cvt_pk_bf16_f32 v144, v132, v133
	v_cvt_pk_bf16_f32 v145, v134, v135
	v_cvt_pk_bf16_f32 v146, v136, v137
	v_cvt_pk_bf16_f32 v147, v138, v139
	global_store_dwordx4 v173, v[144:147], s[4:5] offset:256
	s_branch .LBB0_187
.LBB0_188:
	s_add_i32 s4, s10, -10
	s_cmp_gt_u32 s4, 3
	s_cbranch_scc1 .Lgate_new
	v_mul_f32_e32 v130, 0xbfb8aa3b, v126
	v_mul_f32_e32 v131, 0xbfb8aa3b, v127
	v_mul_f32_e32 v132, 0xbfb8aa3b, v128
	v_mul_f32_e32 v133, 0xbfb8aa3b, v129
	v_mul_f32_e32 v134, 0xbfb8aa3b, v78
	v_mul_f32_e32 v135, 0xbfb8aa3b, v79
	v_mul_f32_e32 v136, 0xbfb8aa3b, v80
	v_mul_f32_e32 v137, 0xbfb8aa3b, v81
	v_mul_f32_e32 v138, 0xbfb8aa3b, v118
	v_mul_f32_e32 v139, 0xbfb8aa3b, v119
	v_mul_f32_e32 v140, 0xbfb8aa3b, v120
	v_mul_f32_e32 v141, 0xbfb8aa3b, v121
	v_mul_f32_e32 v142, 0xbfb8aa3b, v74
	v_mul_f32_e32 v143, 0xbfb8aa3b, v75
	v_mul_f32_e32 v144, 0xbfb8aa3b, v76
	v_mul_f32_e32 v145, 0xbfb8aa3b, v77
	v_mul_f32_e32 v146, 0xbfb8aa3b, v110
	v_mul_f32_e32 v147, 0xbfb8aa3b, v111
	v_mul_f32_e32 v148, 0xbfb8aa3b, v112
	v_mul_f32_e32 v149, 0xbfb8aa3b, v113
	v_mul_f32_e32 v150, 0xbfb8aa3b, v70
	v_mul_f32_e32 v151, 0xbfb8aa3b, v71
	v_mul_f32_e32 v154, 0xbfb8aa3b, v72
	v_mul_f32_e32 v155, 0xbfb8aa3b, v73
	v_mul_f32_e32 v156, 0xbfb8aa3b, v102
	v_mul_f32_e32 v173, 0xbfb8aa3b, v103
	v_mul_f32_e32 v207, 0xbfb8aa3b, v104
	v_mul_f32_e32 v208, 0xbfb8aa3b, v105
	v_mul_f32_e32 v209, 0xbfb8aa3b, v66
	v_mul_f32_e32 v210, 0xbfb8aa3b, v67
	v_mul_f32_e32 v211, 0xbfb8aa3b, v68
	v_mul_f32_e32 v212, 0xbfb8aa3b, v69
	v_mul_f32_e32 v213, 0xbfb8aa3b, v62
	v_mul_f32_e32 v214, 0xbfb8aa3b, v63
	v_mul_f32_e32 v215, 0xbfb8aa3b, v64
	v_mul_f32_e32 v216, 0xbfb8aa3b, v65
	v_mul_f32_e32 v217, 0xbfb8aa3b, v14
	v_mul_f32_e32 v218, 0xbfb8aa3b, v15
	v_exp_f32_e32 v206, v130
	v_exp_f32_e32 v205, v131
	v_exp_f32_e32 v204, v132
	v_exp_f32_e32 v202, v133
	v_exp_f32_e32 v198, v134
	v_exp_f32_e32 v197, v135
	v_exp_f32_e32 v196, v136
	v_exp_f32_e32 v194, v137
	v_exp_f32_e32 v203, v138
	v_exp_f32_e32 v201, v139
	v_exp_f32_e32 v200, v140
	v_exp_f32_e32 v199, v141
	v_exp_f32_e32 v195, v142
	v_exp_f32_e32 v193, v143
	v_exp_f32_e32 v192, v144
	v_exp_f32_e32 v191, v145
	v_exp_f32_e32 v177, v146
	v_exp_f32_e32 v176, v147
	v_exp_f32_e32 v175, v148
	v_exp_f32_e32 v157, v149
	v_exp_f32_e32 v153, v150
	v_exp_f32_e32 v152, v151
	v_exp_f32_e32 v151, v154
	v_exp_f32_e32 v149, v155
	v_exp_f32_e32 v174, v156
	v_exp_f32_e32 v156, v173
	v_exp_f32_e32 v155, v207
	v_exp_f32_e32 v154, v208
	v_exp_f32_e32 v150, v209
	v_exp_f32_e32 v148, v210
	v_exp_f32_e32 v147, v211
	v_exp_f32_e32 v146, v212
	v_exp_f32_e32 v145, v213
	v_exp_f32_e32 v144, v214
	v_exp_f32_e32 v143, v215
	v_exp_f32_e32 v141, v216
	v_exp_f32_e32 v137, v217
	v_exp_f32_e32 v136, v218
	s_add_i32 s4, s10, -10
	s_cmp_gt_u32 s4, 3
	v_mul_f32_e32 v135, 0xbfb8aa3b, v16
	v_mul_f32_e32 v134, 0xbfb8aa3b, v17
	v_mul_f32_e32 v142, 0xbfb8aa3b, v54
	v_mul_f32_e32 v140, 0xbfb8aa3b, v55
	v_mul_f32_e32 v139, 0xbfb8aa3b, v56
	v_mul_f32_e32 v138, 0xbfb8aa3b, v57
	s_branch .LBB0_190
